# grid-barrier poll back-off sweep: s_sleep 6 in the two generation-flag spin loops
# baseline (speedup 1.0000x reference)
.LBB0_1296:
	s_and_b32 s26, s0, 0xff
	s_mov_b64 s[24:25], -1
	s_cmp_lg_u32 s26, 0
	s_mov_b64 s[40:41], -1
	s_sleep 6
	s_cbranch_scc0 .LBB0_1299
	s_and_b64 vcc, exec, s[40:41]
	s_cbranch_vccz .LBB0_1295
